# MIX1 queue: cycles of 9 LRU + 24 attention items, the 128 short sample HGRN items handed out last (short tail)
# baseline (speedup 1.0000x reference)
.Lq_map:
	s_cmpk_ge_u32 s14, 0x4a0
	s_cbranch_scc1 .Lq_end
	s_cmpk_ge_u32 s14, 0x420
	s_cbranch_scc1 .Lq_k2
	s_mul_hi_u32 s12, s14, 0x7c1f07d
	s_mul_i32 s13, s12, 33
	s_sub_i32 s13, s14, s13
	s_cmpk_ge_u32 s13, 9
	s_cbranch_scc1 .Lq_k3
	s_mul_i32 s14, s12, 9
	s_add_i32 s14, s14, s13
	s_branch .Lq_mapped
.Lq_k2:
	s_addk_i32 s14, 0xfe00
	s_branch .Lq_mapped
.Lq_k3:
	s_mul_i32 s14, s12, 24
	s_add_i32 s14, s14, s13
	s_addk_i32 s14, 0x297
	s_branch .Lq_mapped
